# MLA K/V tiles staged by LDS-DMA one tile ahead (SGPR bases + constant per-lane offsets) instead of global_load to VGPR plus ds_write
# speedup vs baseline: 1.0055x; 1.0055x over previous
.LBB0_763:
	s_and_b32 s4, s77, 1
	s_add_i32 s5, s77, s4
	s_sub_i32 s4, 0, s4
	s_xor_b32 s4, s2, s4
	s_mul_i32 s5, s5, s30
	s_add_i32 s4, s5, s4
	s_cmpk_gt_i32 s4, 0x1ff
	s_cbranch_scc1 .LBB0_762
	s_and_b32 s86, s4, 7
	s_mul_i32 s5, s86, 0x180
	s_add_u32 s10, s40, s5
	s_addc_u32 s11, s60, 0
	s_mul_i32 s5, s86, 0x600000
	s_add_u32 s6, s61, s5
	s_addc_u32 s7, s72, 0
	s_lshl_b32 s5, s86, 22
	s_add_u32 s8, s73, s5
	v_mov_b32_e32 v22, v162
	s_addc_u32 s9, s74, 0
	s_lshl_b32 s4, s4, 5
	s_and_b32 s54, s4, 0xffffff00
	v_ashrrev_i32_e32 v0, 1, v22
	v_and_b32_e32 v0, 0xffffffe0, v0
	v_subrev_u32_e32 v38, s54, v0
	v_and_b32_e32 v36, 31, v22
	v_add_u32_e32 v186, 0x3f00, v38
	v_bfe_u32 v37, v22, 5, 1
	v_or_b32_e32 v158, v186, v36
	v_and_b32_e32 v4, 15, v22
	v_bfe_u32 v5, v22, 4, 2
	v_add_u32_e32 v158, v186, v4
	v_lshlrev_b32_e32 v0, 4, v5
	v_mov_b64_e32 v[2:3], s[10:11]
	v_mad_i64_i32 v[2:3], s[4:5], v158, s45, v[2:3]
	v_lshl_add_u64 v[2:3], v[2:3], 0, v[0:1]
	v_add_co_u32_e32 v4, vcc, 0xc000, v2
	s_nop 1
	v_addc_co_u32_e32 v5, vcc, 0, v3, vcc
	global_load_dwordx4 v[82:85], v[2:3], off
	global_load_dwordx4 v[86:89], v[2:3], off offset:64
	global_load_dwordx4 v[90:93], v[2:3], off offset:128
	global_load_dwordx4 v[94:97], v[2:3], off offset:192
	global_load_dwordx4 v[98:101], v[2:3], off offset:256
	global_load_dwordx4 v[102:105], v[2:3], off offset:320
	global_load_dwordx4 v[106:109], v[4:5], off
	global_load_dwordx4 v[110:113], v[4:5], off offset:64
	global_load_dwordx4 v[114:117], v[4:5], off offset:128
	global_load_dwordx4 v[118:121], v[4:5], off offset:192
	global_load_dwordx4 v[122:125], v[4:5], off offset:256
	global_load_dwordx4 v[126:129], v[4:5], off offset:320
	v_add_u32_e32 v24, 0x200, v22
	v_ashrrev_i32_e32 v25, 31, v24
	v_ashrrev_i32_e32 v23, 31, v22
	v_lshrrev_b32_e32 v18, 29, v25
	v_lshrrev_b32_e32 v12, 29, v23
	v_add_u32_e32 v20, v24, v18
	v_add_u32_e32 v14, v22, v12
	v_ashrrev_i32_e32 v32, 3, v20
	v_and_b32_e32 v20, -8, v20
	v_lshlrev_b64 v[166:167], 4, v[24:25]
	v_add_u32_e32 v26, 0x400, v22
	v_ashrrev_i32_e32 v28, 3, v14
	v_and_b32_e32 v14, -8, v14
	v_ashrrev_i32_e32 v33, 31, v32
	v_sub_u32_e32 v25, v24, v20
	v_lshlrev_b64 v[160:161], 4, v[22:23]
	v_ashrrev_i32_e32 v27, 31, v26
	v_ashrrev_i32_e32 v29, 31, v28
	v_sub_u32_e32 v23, v22, v14
	v_lshlrev_b64 v[174:175], 15, v[32:33]
	v_lshlrev_b32_e32 v176, 3, v25
	v_lshlrev_b64 v[168:169], 4, v[26:27]
	v_lshlrev_b64 v[170:171], 15, v[28:29]
	v_lshlrev_b32_e32 v172, 3, v23
	v_lshl_add_u64 v[18:19], s[8:9], 0, v[174:175]
	v_ashrrev_i32_e32 v177, 31, v176
	v_lshl_add_u64 v[2:3], s[6:7], 0, v[160:161]
	v_lshl_add_u64 v[6:7], s[6:7], 0, v[166:167]
	v_lshl_add_u64 v[10:11], s[6:7], 0, v[168:169]
	v_lshl_add_u64 v[12:13], s[8:9], 0, v[170:171]
	v_ashrrev_i32_e32 v173, 31, v172
	v_lshl_add_u64 v[34:35], v[176:177], 1, v[18:19]
	global_load_dwordx4 v[2:5], v[2:3], off
	s_nop 0
	global_load_dwordx4 v[6:9], v[6:7], off
	v_lshl_add_u64 v[30:31], v[172:173], 1, v[12:13]
	global_load_dwordx4 v[10:13], v[10:11], off
	s_nop 0
	global_load_dwordx4 v[14:17], v[30:31], off
	global_load_dwordx4 v[18:21], v[34:35], off
	s_sub_i32 s4, 0x4000, s54
	v_and_b32_e32 v27, 63, v22
	v_ashrrev_i32_e32 v159, 31, v158
	v_mul_hi_i32 v29, v22, s29
	v_lshrrev_b32_e32 v33, 31, v29
	v_ashrrev_i32_e32 v29, 2, v29
	v_add_u32_e32 v29, v29, v33
	v_mul_lo_u32 v187, v29, s48
	v_mul_lo_u32 v29, v29, 24
	v_sub_u32_e32 v22, v22, v29
	v_lshlrev_b32_e32 v188, 4, v22
	v_add3_u32 v22, s78, v187, v188
	s_waitcnt vmcnt(4)
	ds_write_b128 v22, v[2:5]
	v_mul_hi_i32 v2, v24, s29
	v_lshrrev_b32_e32 v3, 31, v2
	v_ashrrev_i32_e32 v2, 2, v2
	v_add_u32_e32 v2, v2, v3
	v_mul_lo_u32 v189, v2, s48
	v_mul_lo_u32 v2, v2, 24
	v_sub_u32_e32 v2, v24, v2
	v_lshlrev_b32_e32 v190, 4, v2
	v_add3_u32 v2, s78, v189, v190
	s_waitcnt vmcnt(3)
	ds_write_b128 v2, v[6:9]
	v_mul_hi_i32 v2, v26, s29
	v_lshrrev_b32_e32 v3, 31, v2
	v_ashrrev_i32_e32 v2, 2, v2
	v_add_u32_e32 v2, v2, v3
	v_mul_lo_u32 v191, v2, s48
	v_mul_lo_u32 v2, v2, 24
	v_sub_u32_e32 v2, v26, v2
	v_lshlrev_b32_e32 v192, 4, v2
	s_movk_i32 s5, 0x90
	v_add3_u32 v2, s78, v191, v192
	v_mul_lo_u32 v193, v28, s5
	v_lshlrev_b32_e32 v194, 4, v23
	s_waitcnt vmcnt(2)
	ds_write_b128 v2, v[10:13]
	v_add3_u32 v2, s78, v193, v194
	v_mul_lo_u32 v195, v32, s5
	v_lshlrev_b32_e32 v196, 4, v25
	s_add_u32 s10, s6, 0x6000
	s_waitcnt vmcnt(1)
	ds_write_b128 v2, v[14:17] offset:51200
	v_add3_u32 v2, s78, v195, v196
	s_addc_u32 s11, s7, 0
	s_waitcnt vmcnt(0)
	ds_write_b128 v2, v[18:21] offset:51200
	s_movk_i32 s49, 0x90
	s_lshr_b32 s87, s4, 6
	v_mul_u32_u24_e32 v2, 0x190, v36
	v_add3_u32 v202, s78, v2, v0
	v_lshlrev_b32_e32 v2, 2, v27
	v_mov_b32_e32 v50, v1
	v_mov_b32_e32 v51, v1
	v_add_u32_e32 v201, 0x3f3f, v38
	v_add_u32_e32 v203, 0x3f1f, v38
	v_lshlrev_b32_e32 v197, 2, v37
	v_xor_b32_e32 v198, 0x80, v2
	v_mul_u32_u24_e32 v200, 0x90, v36
	v_mov_b32_e32 v52, v1
	v_mov_b32_e32 v53, v1
	v_mov_b32_e32 v54, v1
	v_mov_b32_e32 v55, v1
	v_mov_b32_e32 v56, v1
	v_mov_b32_e32 v57, v1
	v_mov_b32_e32 v58, v1
	v_mov_b32_e32 v59, v1
	v_mov_b32_e32 v60, v1
	v_mov_b32_e32 v61, v1
	v_mov_b32_e32 v62, v1
	v_mov_b32_e32 v63, v1
	v_mov_b32_e32 v64, v1
	v_mov_b32_e32 v65, v1
	v_readlane_b32 s5, v246, 59
	v_mov_b64_e32 v[34:35], v[50:51]
	v_mov_b64_e32 v[18:19], v[50:51]
	v_mov_b64_e32 v[2:3], v[50:51]
	s_mov_b32 s4, 0
	v_mov_b32_e32 v199, 0
	v_mov_b32_e32 v206, 0xf149f2ca
	v_mov_b32_e32 v209, s5
	v_mov_b32_e32 v154, 0
	v_mov_b32_e32 v155, 0
	v_mov_b32_e32 v156, 0
	v_mov_b32_e32 v157, 0
	v_mov_b32_e32 v150, 0
	v_mov_b32_e32 v151, 0
	v_mov_b32_e32 v152, 0
	v_mov_b32_e32 v153, 0
	v_mov_b64_e32 v[36:37], v[52:53]
	v_mov_b64_e32 v[38:39], v[54:55]
	v_mov_b64_e32 v[40:41], v[56:57]
	v_mov_b64_e32 v[42:43], v[58:59]
	v_mov_b64_e32 v[44:45], v[60:61]
	v_mov_b64_e32 v[46:47], v[62:63]
	v_mov_b64_e32 v[48:49], v[64:65]
	v_mov_b64_e32 v[20:21], v[52:53]
	v_mov_b64_e32 v[22:23], v[54:55]
	v_mov_b64_e32 v[24:25], v[56:57]
	v_mov_b64_e32 v[26:27], v[58:59]
	v_mov_b64_e32 v[28:29], v[60:61]
	v_mov_b64_e32 v[30:31], v[62:63]
	v_mov_b64_e32 v[32:33], v[64:65]
	v_mov_b64_e32 v[4:5], v[52:53]
	v_mov_b64_e32 v[6:7], v[54:55]
	v_mov_b64_e32 v[8:9], v[56:57]
	v_mov_b64_e32 v[10:11], v[58:59]
	v_mov_b64_e32 v[12:13], v[60:61]
	v_mov_b64_e32 v[14:15], v[62:63]
	v_mov_b64_e32 v[16:17], v[64:65]
	v_and_b32_e32 v239, 15, v162
	v_bfe_u32 v244, v162, 4, 2
	v_lshrrev_b32_e32 v245, 3, v239
	v_lshl_add_u32 v245, v245, 3, v239
	v_mul_u32_u24_e32 v245, 0x190, v245
	v_lshlrev_b32_e32 v205, 4, v244
	v_add3_u32 v202, s78, v245, v205
	v_mul_u32_u24_e32 v245, 0x90, v239
	v_add_u32_e32 v200, v245, v205
	v_lshrrev_b32_e32 v245, 1, v244
	v_lshlrev_b32_e32 v245, 3, v245
	v_lshl_add_u32 v245, v244, 2, v245
	v_sub_u32_e32 v197, v245, v239
	v_and_b32_e32 v245, 63, v162
	v_xor_b32_e32 v245, 16, v245
	v_lshlrev_b32_e32 v208, 2, v245
	v_mov_b32_e32 v206, 0
	v_mov_b32_e32 v201, 0
	v_mov_b32_e32 v203, 0
	s_mov_b32 s21, 0
	v_mov_b32_e32 v210, 0
	v_mov_b32_e32 v211, 0
	v_mov_b32_e32 v212, 0
	v_mov_b32_e32 v213, 0
	v_mov_b32_e32 v214, 0
	v_mov_b32_e32 v215, 0
	v_mov_b32_e32 v216, 0
	v_mov_b32_e32 v217, 0
	v_readfirstlane_b32 s12, v186
	v_add_u32_e32 v244, 0, v162
	v_mul_u32_u24_e32 v245, 0x51f, v244
	v_lshrrev_b32_e32 v245, 15, v245
	v_mul_u32_u24_e32 v239, 25, v245
	v_sub_u32_e32 v244, v244, v239
	v_min_u32_e32 v244, 23, v244
	v_mul_u32_u24_e32 v245, 0x180, v245
	v_lshl_add_u32 v130, v244, 4, v245
	v_add_u32_e32 v244, 512, v162
	v_mul_u32_u24_e32 v245, 0x51f, v244
	v_lshrrev_b32_e32 v245, 15, v245
	v_mul_u32_u24_e32 v239, 25, v245
	v_sub_u32_e32 v244, v244, v239
	v_min_u32_e32 v244, 23, v244
	v_mul_u32_u24_e32 v245, 0x180, v245
	v_lshl_add_u32 v131, v244, 4, v245
	v_add_u32_e32 v244, 1024, v162
	v_mul_u32_u24_e32 v245, 0x51f, v244
	v_lshrrev_b32_e32 v245, 15, v245
	v_mul_u32_u24_e32 v239, 25, v245
	v_sub_u32_e32 v244, v244, v239
	v_min_u32_e32 v244, 23, v244
	v_mul_u32_u24_e32 v245, 0x180, v245
	v_lshl_add_u32 v132, v244, 4, v245
	v_add_u32_e32 v244, 1536, v162
	v_mul_u32_u24_e32 v245, 0x51f, v244
	v_lshrrev_b32_e32 v245, 15, v245
	v_mul_u32_u24_e32 v239, 25, v245
	v_sub_u32_e32 v244, v244, v239
	v_min_u32_e32 v244, 23, v244
	v_mul_u32_u24_e32 v245, 0x180, v245
	v_lshl_add_u32 v133, v244, 4, v245
	v_add_u32_e32 v244, 0, v162
	v_mul_u32_u24_e32 v245, 0x71d, v244
	v_lshrrev_b32_e32 v245, 14, v245
	v_mul_u32_u24_e32 v239, 9, v245
	v_sub_u32_e32 v244, v244, v239
	v_min_u32_e32 v244, 7, v244
	v_lshlrev_b32_e32 v245, 15, v245
	v_lshl_add_u32 v134, v244, 4, v245
	v_add_u32_e32 v244, 512, v162
	v_mul_u32_u24_e32 v245, 0x71d, v244
	v_lshrrev_b32_e32 v245, 14, v245
	v_mul_u32_u24_e32 v239, 9, v245
	v_sub_u32_e32 v244, v244, v239
	v_min_u32_e32 v244, 7, v244
	v_lshlrev_b32_e32 v245, 15, v245
	v_lshl_add_u32 v135, v244, 4, v245
	v_add_u32_e32 v244, 1024, v162
	v_mul_u32_u24_e32 v245, 0x71d, v244
	v_lshrrev_b32_e32 v245, 14, v245
	v_mul_u32_u24_e32 v239, 9, v245
	v_sub_u32_e32 v244, v244, v239
	v_min_u32_e32 v244, 7, v244
	v_lshlrev_b32_e32 v245, 15, v245
	v_lshl_add_u32 v136, v244, 4, v245
	s_nop 3
	s_lshr_b32 s22, s12, 5
	s_and_b32 s22, s22, 7
	s_lshl_b32 s23, s22, 10
	s_waitcnt lgkmcnt(0)
	s_barrier
	s_and_b32 s5, s4, 1
	s_add_i32 s88, s4, 1
	s_cmp_ge_u32 s88, s87
	s_cbranch_scc1 .LBB0_766
.LBB0_765:
	s_xor_b32 s10, s5, 1
	s_mulk_i32 s10, 0x6400
	s_add_i32 s10, s10, s23
	s_addk_i32 s10, 0x400
	s_mul_i32 s11, s88, 0x6000
	s_add_u32 s16, s6, s11
	s_addc_u32 s17, s7, 0
	s_add_u32 m0, s10, 0x0
	s_nop 0
	global_load_lds_dwordx4 v130, s[16:17]
	s_add_u32 m0, s10, 0x2000
	s_nop 0
	global_load_lds_dwordx4 v131, s[16:17]
	s_add_u32 m0, s10, 0x4000
	s_nop 0
	global_load_lds_dwordx4 v132, s[16:17]
	s_cmp_lg_u32 s22, 0
	s_cbranch_scc1 .Lv3_dma_k3
	s_add_u32 m0, s10, 0x6000
	s_nop 0
	global_load_lds_dwordx4 v133, s[16:17]
.Lv3_dma_k3:
	s_mul_hi_u32 s11, s88, 0xaaaaaaab
	s_lshr_b32 s11, s11, 1
	s_mul_i32 s11, s11, 3
	s_sub_i32 s11, s88, s11
	s_mulk_i32 s11, 0x4800
	s_add_i32 s11, s11, s23
	s_add_i32 s11, s11, 0xcc00
	s_lshl_b32 s18, s88, 7
	s_add_u32 s16, s8, s18
	s_addc_u32 s17, s9, 0
	s_add_u32 m0, s11, 0x0
	s_nop 0
	global_load_lds_dwordx4 v134, s[16:17]
	s_add_u32 m0, s11, 0x2000
	s_nop 0
	global_load_lds_dwordx4 v135, s[16:17]
	s_cmp_gt_u32 s22, 1
	s_cbranch_scc1 .Lv3_dma_v2
	s_add_u32 m0, s11, 0x4000
	s_nop 0
	global_load_lds_dwordx4 v136, s[16:17]
.Lv3_dma_v2:
.LBB0_766:
	s_lshl_b32 s54, s4, 6

.LBB0_776:
	s_cmp_eq_u32 s88, s87
	s_waitcnt vmcnt(0) lgkmcnt(0)
	s_barrier
	s_cbranch_scc1 .LBB0_761
	s_mov_b32 s4, s88
	s_and_b32 s5, s4, 1
	s_add_i32 s88, s4, 1
	s_cmp_ge_u32 s88, s87
	s_cbranch_scc0 .LBB0_765
	s_branch .LBB0_766
